# weight conversion loops with gain: issue the 8 gain loads before the next-item prefetch so their waits stop draining the prefetch
# speedup vs baseline: 1.0347x; 1.0060x over previous
; __device__ __forceinline__ void cvt_store(const CvtDesc& d, const CvtPos& p, f32x4 (&v)[8], LAS float* scr, int lane) {
;     ...
;     if (d.gk) {
; #pragma unroll
;         for (int i = 0; i < 8; ++i) v[i] *= d.gk[k0 + 8 * i + rr8]; }
; __device__ __forceinline__ void cvt_run(const CvtDesc& d, LAS unsigned char* lds, int wg, int nwg) {
;     ...
;         f32x4 v[8]; const CvtPos p = pN;
; #pragma unroll
;         for (int i = 0; i < 8; ++i) v[i] = vN[i];
;         if (it + NGW < nitems) { pN = cvt_pos(d, it + NGW); cvt_load(d, pN, vN, lane); }
;         cvt_store(d, p, v, scr, lane);
.LBB0_26:
	s_and_b64 vcc, exec, s[28:29]
	s_cbranch_vccz .Lgk_skip_0
	v_or_b32_e32 v126, v68, v70
	v_ashrrev_i32_e32 v127, 31, v126
	v_lshl_add_u64 v[126:127], v[126:127], 2, s[12:13]
	global_load_dword v110, v[126:127], off
	global_load_dword v112, v[126:127], off offset:32
	global_load_dword v114, v[126:127], off offset:64
	global_load_dword v116, v[126:127], off offset:96
	global_load_dword v118, v[126:127], off offset:128
	global_load_dword v120, v[126:127], off offset:160
	global_load_dword v122, v[126:127], off offset:192
	global_load_dword v124, v[126:127], off offset:224

; __device__ __forceinline__ void cvt_store(const CvtDesc& d, const CvtPos& p, f32x4 (&v)[8], LAS float* scr, int lane) {
;     ...
;     if (d.gk) {
; #pragma unroll
;         for (int i = 0; i < 8; ++i) v[i] *= d.gk[k0 + 8 * i + rr8]; }
.LBB0_28:
	s_or_b64 exec, exec, s[36:37]
	s_andn2_b64 vcc, exec, s[28:29]
	s_cbranch_vccnz .LBB0_25
	s_waitcnt vmcnt(8)
	v_pk_mul_f32 v[62:63], v[62:63], v[110:111] op_sel_hi:[1,0]
	v_pk_mul_f32 v[60:61], v[60:61], v[110:111] op_sel_hi:[1,0]
	v_pk_mul_f32 v[58:59], v[58:59], v[112:113] op_sel_hi:[1,0]
	v_pk_mul_f32 v[56:57], v[56:57], v[112:113] op_sel_hi:[1,0]
	v_pk_mul_f32 v[54:55], v[54:55], v[114:115] op_sel_hi:[1,0]
	v_pk_mul_f32 v[52:53], v[52:53], v[114:115] op_sel_hi:[1,0]
	v_pk_mul_f32 v[50:51], v[50:51], v[116:117] op_sel_hi:[1,0]
	v_pk_mul_f32 v[48:49], v[48:49], v[116:117] op_sel_hi:[1,0]
	v_pk_mul_f32 v[46:47], v[46:47], v[118:119] op_sel_hi:[1,0]
	v_pk_mul_f32 v[44:45], v[44:45], v[118:119] op_sel_hi:[1,0]
	v_pk_mul_f32 v[42:43], v[42:43], v[120:121] op_sel_hi:[1,0]
	v_pk_mul_f32 v[40:41], v[40:41], v[120:121] op_sel_hi:[1,0]
	v_pk_mul_f32 v[38:39], v[38:39], v[122:123] op_sel_hi:[1,0]
	v_pk_mul_f32 v[36:37], v[36:37], v[122:123] op_sel_hi:[1,0]
	v_pk_mul_f32 v[22:23], v[22:23], v[124:125] op_sel_hi:[1,0]
	v_pk_mul_f32 v[20:21], v[20:21], v[124:125] op_sel_hi:[1,0]
	s_branch .LBB0_25
.Lgk_nopref_0:
	s_waitcnt vmcnt(0)
	s_branch .LBB0_28

; __device__ __forceinline__ void cvt_store(const CvtDesc& d, const CvtPos& p, f32x4 (&v)[8], LAS float* scr, int lane) {
;     ...
;     if (d.gk) {
; #pragma unroll
;         for (int i = 0; i < 8; ++i) v[i] *= d.gk[k0 + 8 * i + rr8]; }
; __device__ __forceinline__ void cvt_run(const CvtDesc& d, LAS unsigned char* lds, int wg, int nwg) {
;     ...
;         f32x4 v[8]; const CvtPos p = pN;
; #pragma unroll
;         for (int i = 0; i < 8; ++i) v[i] = vN[i];
;         if (it + NGW < nitems) { pN = cvt_pos(d, it + NGW); cvt_load(d, pN, vN, lane); }
;         cvt_store(d, p, v, scr, lane);
.LBB0_106:
	s_and_b64 vcc, exec, s[24:25]
	s_cbranch_vccz .Lgk_skip_1
	v_or_b32_e32 v126, v72, v69
	v_ashrrev_i32_e32 v127, 31, v126
	v_lshl_add_u64 v[126:127], v[126:127], 2, s[12:13]
	global_load_dword v110, v[126:127], off
	global_load_dword v112, v[126:127], off offset:32
	global_load_dword v114, v[126:127], off offset:64
	global_load_dword v116, v[126:127], off offset:96
	global_load_dword v118, v[126:127], off offset:128
	global_load_dword v120, v[126:127], off offset:160
	global_load_dword v122, v[126:127], off offset:192
	global_load_dword v124, v[126:127], off offset:224

; __device__ __forceinline__ void cvt_store(const CvtDesc& d, const CvtPos& p, f32x4 (&v)[8], LAS float* scr, int lane) {
;     ...
;     if (d.gk) {
; #pragma unroll
;         for (int i = 0; i < 8; ++i) v[i] *= d.gk[k0 + 8 * i + rr8]; }
.LBB0_110:
	s_or_b64 exec, exec, s[26:27]
	s_and_b64 s[4:5], exec, s[4:5]
	s_or_b64 s[22:23], s[4:5], s[22:23]
	s_andn2_b64 vcc, exec, s[24:25]
	s_cbranch_vccnz .LBB0_105
	s_waitcnt vmcnt(8)
	v_pk_mul_f32 v[62:63], v[62:63], v[110:111] op_sel_hi:[1,0]
	v_pk_mul_f32 v[60:61], v[60:61], v[110:111] op_sel_hi:[1,0]
	v_pk_mul_f32 v[58:59], v[58:59], v[112:113] op_sel_hi:[1,0]
	v_pk_mul_f32 v[56:57], v[56:57], v[112:113] op_sel_hi:[1,0]
	v_pk_mul_f32 v[50:51], v[50:51], v[114:115] op_sel_hi:[1,0]
	v_pk_mul_f32 v[48:49], v[48:49], v[114:115] op_sel_hi:[1,0]
	v_pk_mul_f32 v[54:55], v[54:55], v[116:117] op_sel_hi:[1,0]
	v_pk_mul_f32 v[52:53], v[52:53], v[116:117] op_sel_hi:[1,0]
	v_pk_mul_f32 v[46:47], v[46:47], v[118:119] op_sel_hi:[1,0]
	v_pk_mul_f32 v[44:45], v[44:45], v[118:119] op_sel_hi:[1,0]
	v_pk_mul_f32 v[30:31], v[30:31], v[120:121] op_sel_hi:[1,0]
	v_pk_mul_f32 v[28:29], v[28:29], v[120:121] op_sel_hi:[1,0]
	v_pk_mul_f32 v[18:19], v[18:19], v[122:123] op_sel_hi:[1,0]
	v_pk_mul_f32 v[16:17], v[16:17], v[122:123] op_sel_hi:[1,0]
	v_pk_mul_f32 v[42:43], v[42:43], v[124:125] op_sel_hi:[1,0]
	v_pk_mul_f32 v[40:41], v[40:41], v[124:125] op_sel_hi:[1,0]
	s_branch .LBB0_105

; __device__ __forceinline__ void cvt_store(const CvtDesc& d, const CvtPos& p, f32x4 (&v)[8], LAS float* scr, int lane) {
;     ...
;     if (d.gk) {
; #pragma unroll
;         for (int i = 0; i < 8; ++i) v[i] *= d.gk[k0 + 8 * i + rr8]; }
; __device__ __forceinline__ void cvt_run(const CvtDesc& d, LAS unsigned char* lds, int wg, int nwg) {
;     ...
;         f32x4 v[8]; const CvtPos p = pN;
; #pragma unroll
;         for (int i = 0; i < 8; ++i) v[i] = vN[i];
;         if (it + NGW < nitems) { pN = cvt_pos(d, it + NGW); cvt_load(d, pN, vN, lane); }
;         cvt_store(d, p, v, scr, lane);
.LBB0_120:
	s_and_b64 vcc, exec, s[26:27]
	s_cbranch_vccz .Lgk_skip_2
	v_or_b32_e32 v126, v68, v70
	v_ashrrev_i32_e32 v127, 31, v126
	v_lshl_add_u64 v[126:127], v[126:127], 2, s[12:13]
	global_load_dword v110, v[126:127], off
	global_load_dword v112, v[126:127], off offset:32
	global_load_dword v114, v[126:127], off offset:64
	global_load_dword v116, v[126:127], off offset:96
	global_load_dword v118, v[126:127], off offset:128
	global_load_dword v120, v[126:127], off offset:160
	global_load_dword v122, v[126:127], off offset:192
	global_load_dword v124, v[126:127], off offset:224

; __device__ __forceinline__ void cvt_store(const CvtDesc& d, const CvtPos& p, f32x4 (&v)[8], LAS float* scr, int lane) {
;     ...
;     if (d.gk) {
; #pragma unroll
;         for (int i = 0; i < 8; ++i) v[i] *= d.gk[k0 + 8 * i + rr8]; }
.LBB0_122:
	s_or_b64 exec, exec, s[28:29]
	s_andn2_b64 vcc, exec, s[26:27]
	s_cbranch_vccnz .LBB0_119
	s_waitcnt vmcnt(8)
	v_pk_mul_f32 v[62:63], v[62:63], v[110:111] op_sel_hi:[1,0]
	v_pk_mul_f32 v[60:61], v[60:61], v[110:111] op_sel_hi:[1,0]
	v_pk_mul_f32 v[58:59], v[58:59], v[112:113] op_sel_hi:[1,0]
	v_pk_mul_f32 v[56:57], v[56:57], v[112:113] op_sel_hi:[1,0]
	v_pk_mul_f32 v[54:55], v[54:55], v[114:115] op_sel_hi:[1,0]
	v_pk_mul_f32 v[52:53], v[52:53], v[114:115] op_sel_hi:[1,0]
	v_pk_mul_f32 v[50:51], v[50:51], v[116:117] op_sel_hi:[1,0]
	v_pk_mul_f32 v[48:49], v[48:49], v[116:117] op_sel_hi:[1,0]
	v_pk_mul_f32 v[46:47], v[46:47], v[118:119] op_sel_hi:[1,0]
	v_pk_mul_f32 v[44:45], v[44:45], v[118:119] op_sel_hi:[1,0]
	v_pk_mul_f32 v[42:43], v[42:43], v[120:121] op_sel_hi:[1,0]
	v_pk_mul_f32 v[40:41], v[40:41], v[120:121] op_sel_hi:[1,0]
	v_pk_mul_f32 v[38:39], v[38:39], v[122:123] op_sel_hi:[1,0]
	v_pk_mul_f32 v[36:37], v[36:37], v[122:123] op_sel_hi:[1,0]
	v_pk_mul_f32 v[26:27], v[26:27], v[124:125] op_sel_hi:[1,0]
	v_pk_mul_f32 v[24:25], v[24:25], v[124:125] op_sel_hi:[1,0]
	s_branch .LBB0_119

; __device__ __forceinline__ void cvt_store(const CvtDesc& d, const CvtPos& p, f32x4 (&v)[8], LAS float* scr, int lane) {
;     ...
;     if (d.gk) {
; #pragma unroll
;         for (int i = 0; i < 8; ++i) v[i] *= d.gk[k0 + 8 * i + rr8]; }
; __device__ __forceinline__ void cvt_run(const CvtDesc& d, LAS unsigned char* lds, int wg, int nwg) {
;     ...
;         f32x4 v[8]; const CvtPos p = pN;
; #pragma unroll
;         for (int i = 0; i < 8; ++i) v[i] = vN[i];
;         if (it + NGW < nitems) { pN = cvt_pos(d, it + NGW); cvt_load(d, pN, vN, lane); }
;         cvt_store(d, p, v, scr, lane);
.LBB0_132:
	s_and_b64 vcc, exec, s[24:25]
	s_cbranch_vccz .Lgk_skip_3
	v_or_b32_e32 v126, v70, v75
	v_ashrrev_i32_e32 v127, 31, v126
	v_lshl_add_u64 v[126:127], v[126:127], 2, s[12:13]
	global_load_dword v110, v[126:127], off
	global_load_dword v112, v[126:127], off offset:32
	global_load_dword v114, v[126:127], off offset:64
	global_load_dword v116, v[126:127], off offset:96
	global_load_dword v118, v[126:127], off offset:128
	global_load_dword v120, v[126:127], off offset:160
	global_load_dword v122, v[126:127], off offset:192
	global_load_dword v124, v[126:127], off offset:224

; __device__ __forceinline__ void cvt_store(const CvtDesc& d, const CvtPos& p, f32x4 (&v)[8], LAS float* scr, int lane) {
;     ...
;     if (d.gk) {
; #pragma unroll
;         for (int i = 0; i < 8; ++i) v[i] *= d.gk[k0 + 8 * i + rr8]; }
.LBB0_134:
	s_or_b64 exec, exec, s[26:27]
	s_andn2_b64 vcc, exec, s[24:25]
	s_cbranch_vccnz .LBB0_131
	s_waitcnt vmcnt(8)
	v_pk_mul_f32 v[62:63], v[62:63], v[110:111] op_sel_hi:[1,0]
	v_pk_mul_f32 v[60:61], v[60:61], v[110:111] op_sel_hi:[1,0]
	v_pk_mul_f32 v[58:59], v[58:59], v[112:113] op_sel_hi:[1,0]
	v_pk_mul_f32 v[56:57], v[56:57], v[112:113] op_sel_hi:[1,0]
	v_pk_mul_f32 v[54:55], v[54:55], v[114:115] op_sel_hi:[1,0]
	v_pk_mul_f32 v[52:53], v[52:53], v[114:115] op_sel_hi:[1,0]
	v_pk_mul_f32 v[50:51], v[50:51], v[116:117] op_sel_hi:[1,0]
	v_pk_mul_f32 v[48:49], v[48:49], v[116:117] op_sel_hi:[1,0]
	v_pk_mul_f32 v[46:47], v[46:47], v[118:119] op_sel_hi:[1,0]
	v_pk_mul_f32 v[44:45], v[44:45], v[118:119] op_sel_hi:[1,0]
	v_pk_mul_f32 v[42:43], v[42:43], v[120:121] op_sel_hi:[1,0]
	v_pk_mul_f32 v[40:41], v[40:41], v[120:121] op_sel_hi:[1,0]
	v_pk_mul_f32 v[38:39], v[38:39], v[122:123] op_sel_hi:[1,0]
	v_pk_mul_f32 v[36:37], v[36:37], v[122:123] op_sel_hi:[1,0]
	v_pk_mul_f32 v[26:27], v[26:27], v[124:125] op_sel_hi:[1,0]
	v_pk_mul_f32 v[24:25], v[24:25], v[124:125] op_sel_hi:[1,0]
	s_branch .LBB0_131
